# ret phase: K-tile loads issued together (counted vmcnt) + pipelined LDS fragment reads in QK and hp sections
# baseline (speedup 1.0000x reference)
.LBB0_660:
	s_and_b32 s31, s48, 3
	v_readlane_b32 s6, v253, 4
	s_ashr_i32 s30, s48, 2
	s_or_b32 s96, s31, s6
	v_readlane_b32 s52, v251, 16
	s_lshl_b32 s14, s30, 7
	s_lshl_b64 s[6:7], s[96:97], 2
	v_readlane_b32 s56, v251, 20
	v_readlane_b32 s57, v251, 21
	s_add_u32 s6, s56, s6
	s_addc_u32 s7, s57, s7
	v_add_u32_e32 v146, s14, v115
	v_mov_b64_e32 v[0:1], s[68:69]
	global_load_dword v55, v33, s[6:7]
	global_load_dword v54, v33, s[6:7] offset:16
	v_mad_i64_i32 v[148:149], s[6:7], v146, s33, v[0:1]
	s_lshl_b32 s96, s31, 8
	v_lshl_add_u64 v[0:1], v[148:149], 0, s[96:97]
	v_lshlrev_b32_e32 v144, 1, v114
	v_mov_b32_e32 v145, v33
	v_lshl_add_u64 v[0:1], v[0:1], 0, v[144:145]
	global_load_dwordx4 v[34:37], v[0:1], off offset:1024
	global_load_dwordx4 v[38:41], v[0:1], off offset:1088
	global_load_dwordx4 v[42:45], v[0:1], off offset:1152
	global_load_dwordx4 v[46:49], v[0:1], off offset:1216
	v_lshl_add_u64 v[4:5], v[116:117], 0, s[96:97]
	v_add_u32_e32 v8, s14, v118
	v_mad_i64_i32 v[8:9], s[6:7], v8, s33, v[4:5]
	v_add_u32_e32 v12, s14, v120
	v_mad_i64_i32 v[12:13], s[6:7], v12, s33, v[4:5]
	v_add_u32_e32 v16, s14, v122
	v_mad_i64_i32 v[16:17], s[6:7], v16, s33, v[4:5]
	v_add_u32_e32 v20, s14, v124
	v_mad_i64_i32 v[20:21], s[6:7], v20, s33, v[4:5]
	global_load_dwordx4 v[8:11], v[8:9], off
	global_load_dwordx4 v[12:15], v[12:13], off
	global_load_dwordx4 v[16:19], v[16:17], off
	global_load_dwordx4 v[20:23], v[20:21], off
	s_ashr_i32 s15, s14, 31
	v_add_u32_e32 v56, v150, v156
	v_readlane_b32 s22, v254, 27
	v_readlane_b32 s23, v254, 28
	v_readlane_b32 s53, v251, 17
	v_readlane_b32 s54, v251, 18
	v_readlane_b32 s55, v251, 19
	v_readlane_b32 s58, v251, 22
	v_readlane_b32 s59, v251, 23
	v_readlane_b32 s60, v251, 24
	v_readlane_b32 s61, v251, 25
	v_readlane_b32 s62, v251, 26
	v_readlane_b32 s63, v251, 27
	v_readlane_b32 s64, v251, 28
	v_readlane_b32 s65, v251, 29
	v_readlane_b32 s66, v251, 30
	v_readlane_b32 s67, v251, 31
	v_readlane_b32 s6, v252, 15
	v_readlane_b32 s7, v252, 16
	s_lshl_b64 s[14:15], s[14:15], 1
	s_nop 1
	v_mov_b64_e32 v[0:1], s[6:7]
	v_mov_b32_e32 v2, 0x8200
	v_mad_u64_u32 v[0:1], s[6:7], s96, v2, v[0:1]
	v_lshl_add_u64 v[0:1], v[0:1], 0, s[14:15]
	v_lshl_add_u64 v[0:1], v[0:1], 0, v[32:33]
	v_lshl_add_u64 v[2:3], v[0:1], 0, v[126:127]
	global_load_dwordx4 v[66:69], v[2:3], off
	v_lshl_add_u64 v[2:3], v[0:1], 0, v[128:129]
	global_load_dwordx4 v[62:65], v[2:3], off
	v_lshl_add_u64 v[2:3], v[0:1], 0, v[130:131]
	v_lshl_add_u64 v[0:1], v[0:1], 0, v[132:133]
	global_load_dwordx4 v[58:61], v[2:3], off
	global_load_dwordx4 v[50:53], v[0:1], off
	s_waitcnt vmcnt(7)
	v_mul_f32_e32 v54, 0x3fb8aa3b, v54
	ds_write_b128 v119, v[8:11]
	s_waitcnt vmcnt(6)
	ds_write_b128 v121, v[12:15]
	s_waitcnt vmcnt(5)
	ds_write_b128 v123, v[16:19]
	s_waitcnt vmcnt(4)
	ds_write_b128 v125, v[20:23]
	s_waitcnt lgkmcnt(0)
	s_barrier
	ds_read_b128 v[74:77], v56
	ds_read_b128 v[78:81], v56 offset:64
	ds_read_b128 v[82:85], v56 offset:128
	ds_read_b128 v[86:89], v56 offset:192
	ds_read_b128 v[90:93], v56 offset:4352
	ds_read_b128 v[94:97], v56 offset:4416
	ds_read_b128 v[240:243], v56 offset:4480
	ds_read_b128 v[244:247], v56 offset:4544
	s_waitcnt lgkmcnt(7)
	v_mfma_f32_16x16x32_f16 v[28:31], v[74:77], v[34:37], 0
	ds_read_b128 v[74:77], v56 offset:8704
	s_waitcnt lgkmcnt(7)
	v_mfma_f32_16x16x32_f16 v[28:31], v[78:81], v[38:41], v[28:31]
	ds_read_b128 v[78:81], v56 offset:8768
	s_waitcnt lgkmcnt(7)
	v_mfma_f32_16x16x32_f16 v[28:31], v[82:85], v[42:45], v[28:31]
	ds_read_b128 v[82:85], v56 offset:8832
	s_waitcnt lgkmcnt(7)
	v_mfma_f32_16x16x32_f16 v[28:31], v[86:89], v[46:49], v[28:31]
	ds_read_b128 v[86:89], v56 offset:8896
	s_waitcnt lgkmcnt(7)
	v_mfma_f32_16x16x32_f16 v[24:27], v[90:93], v[34:37], 0
	ds_read_b128 v[90:93], v56 offset:13056
	s_waitcnt lgkmcnt(7)
	v_mfma_f32_16x16x32_f16 v[24:27], v[94:97], v[38:41], v[24:27]
	ds_read_b128 v[94:97], v56 offset:13120
	s_waitcnt lgkmcnt(7)
	v_mfma_f32_16x16x32_f16 v[24:27], v[240:243], v[42:45], v[24:27]
	ds_read_b128 v[240:243], v56 offset:13184
	s_waitcnt lgkmcnt(7)
	v_mfma_f32_16x16x32_f16 v[24:27], v[244:247], v[46:49], v[24:27]
	ds_read_b128 v[244:247], v56 offset:13248
	s_waitcnt lgkmcnt(7)
	v_mfma_f32_16x16x32_f16 v[20:23], v[74:77], v[34:37], 0
	ds_read_b128 v[74:77], v56 offset:17408
	s_waitcnt lgkmcnt(7)
	v_mfma_f32_16x16x32_f16 v[20:23], v[78:81], v[38:41], v[20:23]
	ds_read_b128 v[78:81], v56 offset:17472
	s_waitcnt lgkmcnt(7)
	v_mfma_f32_16x16x32_f16 v[20:23], v[82:85], v[42:45], v[20:23]
	ds_read_b128 v[82:85], v56 offset:17536
	s_waitcnt lgkmcnt(7)
	v_mfma_f32_16x16x32_f16 v[20:23], v[86:89], v[46:49], v[20:23]
	ds_read_b128 v[86:89], v56 offset:17600
	s_waitcnt lgkmcnt(7)
	v_mfma_f32_16x16x32_f16 v[16:19], v[90:93], v[34:37], 0
	ds_read_b128 v[90:93], v56 offset:21760
	s_waitcnt lgkmcnt(7)
	v_mfma_f32_16x16x32_f16 v[16:19], v[94:97], v[38:41], v[16:19]
	ds_read_b128 v[94:97], v56 offset:21824
	s_waitcnt lgkmcnt(7)
	v_mfma_f32_16x16x32_f16 v[16:19], v[240:243], v[42:45], v[16:19]
	ds_read_b128 v[240:243], v56 offset:21888
	s_waitcnt lgkmcnt(7)
	v_mfma_f32_16x16x32_f16 v[16:19], v[244:247], v[46:49], v[16:19]
	ds_read_b128 v[244:247], v56 offset:21952
	s_waitcnt lgkmcnt(7)
	v_mfma_f32_16x16x32_f16 v[8:11], v[74:77], v[34:37], 0
	ds_read_b128 v[74:77], v56 offset:26112
	s_waitcnt lgkmcnt(7)
	v_mfma_f32_16x16x32_f16 v[8:11], v[78:81], v[38:41], v[8:11]
	ds_read_b128 v[78:81], v56 offset:26176
	s_waitcnt lgkmcnt(7)
	v_mfma_f32_16x16x32_f16 v[8:11], v[82:85], v[42:45], v[8:11]
	ds_read_b128 v[82:85], v56 offset:26240
	s_waitcnt lgkmcnt(7)
	v_mfma_f32_16x16x32_f16 v[8:11], v[86:89], v[46:49], v[8:11]
	ds_read_b128 v[86:89], v56 offset:26304
	s_waitcnt lgkmcnt(7)
	v_mfma_f32_16x16x32_f16 v[12:15], v[90:93], v[34:37], 0
	ds_read_b128 v[90:93], v56 offset:30464
	s_waitcnt lgkmcnt(7)
	v_mfma_f32_16x16x32_f16 v[12:15], v[94:97], v[38:41], v[12:15]
	ds_read_b128 v[94:97], v56 offset:30528
	s_waitcnt lgkmcnt(7)
	v_mfma_f32_16x16x32_f16 v[12:15], v[240:243], v[42:45], v[12:15]
	ds_read_b128 v[240:243], v56 offset:30592
	s_waitcnt lgkmcnt(7)
	v_mfma_f32_16x16x32_f16 v[12:15], v[244:247], v[46:49], v[12:15]
	ds_read_b128 v[244:247], v56 offset:30656
	s_waitcnt lgkmcnt(7)
	v_mfma_f32_16x16x32_f16 v[4:7], v[74:77], v[34:37], 0
	s_waitcnt lgkmcnt(6)
	v_mfma_f32_16x16x32_f16 v[4:7], v[78:81], v[38:41], v[4:7]
	s_waitcnt lgkmcnt(5)
	v_mfma_f32_16x16x32_f16 v[4:7], v[82:85], v[42:45], v[4:7]
	s_waitcnt lgkmcnt(4)
	v_mfma_f32_16x16x32_f16 v[4:7], v[86:89], v[46:49], v[4:7]
	s_waitcnt lgkmcnt(3)
	v_mfma_f32_16x16x32_f16 v[0:3], v[90:93], v[34:37], 0
	s_waitcnt lgkmcnt(2)
	v_mfma_f32_16x16x32_f16 v[0:3], v[94:97], v[38:41], v[0:3]
	s_waitcnt lgkmcnt(1)
	v_mfma_f32_16x16x32_f16 v[0:3], v[240:243], v[42:45], v[0:3]
	s_waitcnt lgkmcnt(0)
	v_mfma_f32_16x16x32_f16 v[0:3], v[244:247], v[46:49], v[0:3]
	s_nop 7
	s_and_saveexec_b64 s[6:7], s[22:23]
	s_xor_b64 s[22:23], exec, s[6:7]
	s_cbranch_execz .LBB0_662
	v_mul_f32_e32 v56, v54, v157
	v_exp_f32_e32 v56, v56
	v_readlane_b32 s6, v254, 29
	v_readlane_b32 s7, v254, 30
	s_nop 1
	v_cndmask_b32_e64 v56, v56, 2.0, s[6:7]

.LBB0_789:
	s_waitcnt lgkmcnt(0)
	s_barrier
	ds_read_b128 v[240:243], v238
	ds_read_b128 v[244:247], v238 offset:64
	s_add_i32 s56, s56, 1
	s_cmp_eq_u32 s56, 3
	s_waitcnt lgkmcnt(1)
	v_mfma_f32_16x16x32_f16 v[28:31], v[240:243], v[98:101], v[28:31]
	ds_read_b128 v[240:243], v238 offset:128
	s_waitcnt lgkmcnt(1)
	v_mfma_f32_16x16x32_f16 v[28:31], v[244:247], v[102:105], v[28:31]
	ds_read_b128 v[244:247], v238 offset:192
	s_waitcnt lgkmcnt(1)
	v_mfma_f32_16x16x32_f16 v[28:31], v[240:243], v[106:109], v[28:31]
	ds_read_b128 v[240:243], v238 offset:4352
	s_waitcnt lgkmcnt(1)
	v_mfma_f32_16x16x32_f16 v[28:31], v[244:247], v[110:113], v[28:31]
	ds_read_b128 v[244:247], v238 offset:4416
	s_waitcnt lgkmcnt(1)
	v_mfma_f32_16x16x32_f16 v[24:27], v[240:243], v[98:101], v[24:27]
	ds_read_b128 v[240:243], v238 offset:4480
	s_waitcnt lgkmcnt(1)
	v_mfma_f32_16x16x32_f16 v[24:27], v[244:247], v[102:105], v[24:27]
	ds_read_b128 v[244:247], v238 offset:4544
	s_waitcnt lgkmcnt(1)
	v_mfma_f32_16x16x32_f16 v[24:27], v[240:243], v[106:109], v[24:27]
	ds_read_b128 v[240:243], v238 offset:8704
	s_waitcnt lgkmcnt(1)
	v_mfma_f32_16x16x32_f16 v[24:27], v[244:247], v[110:113], v[24:27]
	ds_read_b128 v[244:247], v238 offset:8768
	s_waitcnt lgkmcnt(1)
	v_mfma_f32_16x16x32_f16 v[20:23], v[240:243], v[98:101], v[20:23]
	ds_read_b128 v[240:243], v238 offset:8832
	s_waitcnt lgkmcnt(1)
	v_mfma_f32_16x16x32_f16 v[20:23], v[244:247], v[102:105], v[20:23]
	ds_read_b128 v[244:247], v238 offset:8896
	s_waitcnt lgkmcnt(1)
	v_mfma_f32_16x16x32_f16 v[20:23], v[240:243], v[106:109], v[20:23]
	ds_read_b128 v[240:243], v238 offset:13056
	s_waitcnt lgkmcnt(1)
	v_mfma_f32_16x16x32_f16 v[20:23], v[244:247], v[110:113], v[20:23]
	ds_read_b128 v[244:247], v238 offset:13120
	s_waitcnt lgkmcnt(1)
	v_mfma_f32_16x16x32_f16 v[16:19], v[240:243], v[98:101], v[16:19]
	ds_read_b128 v[240:243], v238 offset:13184
	s_waitcnt lgkmcnt(1)
	v_mfma_f32_16x16x32_f16 v[16:19], v[244:247], v[102:105], v[16:19]
	ds_read_b128 v[244:247], v238 offset:13248
	s_waitcnt lgkmcnt(1)
	v_mfma_f32_16x16x32_f16 v[16:19], v[240:243], v[106:109], v[16:19]
	ds_read_b128 v[240:243], v238 offset:17408
	s_waitcnt lgkmcnt(1)
	v_mfma_f32_16x16x32_f16 v[16:19], v[244:247], v[110:113], v[16:19]
	ds_read_b128 v[244:247], v238 offset:17472
	s_waitcnt lgkmcnt(1)
	v_mfma_f32_16x16x32_f16 v[12:15], v[240:243], v[98:101], v[12:15]
	ds_read_b128 v[240:243], v238 offset:17536
	s_waitcnt lgkmcnt(1)
	v_mfma_f32_16x16x32_f16 v[12:15], v[244:247], v[102:105], v[12:15]
	ds_read_b128 v[244:247], v238 offset:17600
	s_waitcnt lgkmcnt(1)
	v_mfma_f32_16x16x32_f16 v[12:15], v[240:243], v[106:109], v[12:15]
	ds_read_b128 v[240:243], v238 offset:21760
	s_waitcnt lgkmcnt(1)
	v_mfma_f32_16x16x32_f16 v[12:15], v[244:247], v[110:113], v[12:15]
	ds_read_b128 v[244:247], v238 offset:21824
	s_waitcnt lgkmcnt(1)
	v_mfma_f32_16x16x32_f16 v[8:11], v[240:243], v[98:101], v[8:11]
	ds_read_b128 v[240:243], v238 offset:21888
	s_waitcnt lgkmcnt(1)
	v_mfma_f32_16x16x32_f16 v[8:11], v[244:247], v[102:105], v[8:11]
	ds_read_b128 v[244:247], v238 offset:21952
	s_waitcnt lgkmcnt(1)
	v_mfma_f32_16x16x32_f16 v[8:11], v[240:243], v[106:109], v[8:11]
	ds_read_b128 v[240:243], v238 offset:26112
	s_waitcnt lgkmcnt(1)
	v_mfma_f32_16x16x32_f16 v[8:11], v[244:247], v[110:113], v[8:11]
	ds_read_b128 v[244:247], v238 offset:26176
	s_waitcnt lgkmcnt(1)
	v_mfma_f32_16x16x32_f16 v[4:7], v[240:243], v[98:101], v[4:7]
	ds_read_b128 v[240:243], v238 offset:26240
	s_waitcnt lgkmcnt(1)
	v_mfma_f32_16x16x32_f16 v[4:7], v[244:247], v[102:105], v[4:7]
	ds_read_b128 v[244:247], v238 offset:26304
	s_waitcnt lgkmcnt(1)
	v_mfma_f32_16x16x32_f16 v[4:7], v[240:243], v[106:109], v[4:7]
	ds_read_b128 v[240:243], v238 offset:30464
	s_waitcnt lgkmcnt(1)
	v_mfma_f32_16x16x32_f16 v[4:7], v[244:247], v[110:113], v[4:7]
	ds_read_b128 v[244:247], v238 offset:30528
	s_waitcnt lgkmcnt(1)
	v_mfma_f32_16x16x32_f16 v[0:3], v[240:243], v[98:101], v[0:3]
	ds_read_b128 v[240:243], v238 offset:30592
	s_waitcnt lgkmcnt(1)
	v_mfma_f32_16x16x32_f16 v[0:3], v[244:247], v[102:105], v[0:3]
	ds_read_b128 v[244:247], v238 offset:30656
	s_waitcnt lgkmcnt(1)
	v_mfma_f32_16x16x32_f16 v[0:3], v[240:243], v[106:109], v[0:3]
	s_waitcnt lgkmcnt(0)
	v_mfma_f32_16x16x32_f16 v[0:3], v[244:247], v[110:113], v[0:3]
	s_cbranch_scc1 .LBB0_659

.LBB0_794:
	s_add_i32 s14, s7, s56
	s_add_i32 vcc_lo, s14, -1
	s_ashr_i32 vcc_hi, vcc_lo, 31
	s_lshl_b64 vcc, vcc, 16
	s_add_u32 s15, s92, vcc_lo
	s_addc_u32 s31, s93, vcc_hi
	v_add_u32_e32 v222, v230, v231
	s_add_u32 s15, s15, 0x8000
	s_waitcnt vmcnt(3)
	ds_write_b128 v222, v[66:69]
	v_add_u32_e32 v66, v230, v232
	s_addc_u32 s31, s31, 0
	s_waitcnt vmcnt(2)
	ds_write_b128 v66, v[62:65]
	v_add_u32_e32 v62, v230, v233
	s_and_b64 s[22:23], s[22:23], exec
	s_waitcnt vmcnt(1)
	ds_write_b128 v62, v[58:61]
	v_add_u32_e32 v58, v230, v234
	s_cselect_b32 s23, s6, s31
	s_cselect_b32 s22, s57, s15
	s_waitcnt vmcnt(0)
	ds_write_b128 v58, v[50:53]
	v_lshl_add_u64 v[66:67], s[22:23], 0, v[32:33]
	v_mad_i64_i32 v[50:51], s[22:23], s30, v124, 0
	v_mad_i64_i32 v[58:59], s[22:23], s30, v122, 0
	v_mad_i64_i32 v[62:63], s[22:23], s30, v120, 0
	v_mad_i64_i32 v[68:69], s[22:23], s30, v118, 0
	v_lshl_add_u64 v[50:51], v[50:51], 1, v[66:67]
	v_lshl_add_u64 v[58:59], v[58:59], 1, v[66:67]
	v_lshl_add_u64 v[62:63], v[62:63], 1, v[66:67]
	v_lshl_add_u64 v[66:67], v[68:69], 1, v[66:67]
	global_load_dwordx4 v[50:53], v[50:51], off
	v_add_u32_e32 v222, v235, v231
	global_load_dwordx4 v[58:61], v[58:59], off
	s_cmp_lt_u32 s56, 2
	global_load_dwordx4 v[62:65], v[62:63], off
	s_nop 0
	global_load_dwordx4 v[66:69], v[66:67], off
	s_waitcnt lgkmcnt(0)
	s_barrier
	ds_read_b128 v[240:243], v237
	ds_read_b128 v[244:247], v237 offset:64
	s_waitcnt lgkmcnt(1)
	v_mfma_f32_16x16x32_f16 v[94:97], v[240:243], v[98:101], v[94:97]
	ds_read_b128 v[240:243], v237 offset:128
	s_waitcnt lgkmcnt(1)
	v_mfma_f32_16x16x32_f16 v[94:97], v[244:247], v[102:105], v[94:97]
	ds_read_b128 v[244:247], v237 offset:192
	s_waitcnt lgkmcnt(1)
	v_mfma_f32_16x16x32_f16 v[94:97], v[240:243], v[106:109], v[94:97]
	ds_read_b128 v[240:243], v237 offset:4352
	s_waitcnt lgkmcnt(1)
	v_mfma_f32_16x16x32_f16 v[94:97], v[244:247], v[110:113], v[94:97]
	ds_read_b128 v[244:247], v237 offset:4416
	s_waitcnt lgkmcnt(1)
	v_mfma_f32_16x16x32_f16 v[90:93], v[240:243], v[98:101], v[90:93]
	ds_read_b128 v[240:243], v237 offset:4480
	s_waitcnt lgkmcnt(1)
	v_mfma_f32_16x16x32_f16 v[90:93], v[244:247], v[102:105], v[90:93]
	ds_read_b128 v[244:247], v237 offset:4544
	s_waitcnt lgkmcnt(1)
	v_mfma_f32_16x16x32_f16 v[90:93], v[240:243], v[106:109], v[90:93]
	ds_read_b128 v[240:243], v237 offset:8704
	s_waitcnt lgkmcnt(1)
	v_mfma_f32_16x16x32_f16 v[90:93], v[244:247], v[110:113], v[90:93]
	ds_read_b128 v[244:247], v237 offset:8768
	s_waitcnt lgkmcnt(1)
	v_mfma_f32_16x16x32_f16 v[86:89], v[240:243], v[98:101], v[86:89]
	ds_read_b128 v[240:243], v237 offset:8832
	s_waitcnt lgkmcnt(1)
	v_mfma_f32_16x16x32_f16 v[86:89], v[244:247], v[102:105], v[86:89]
	ds_read_b128 v[244:247], v237 offset:8896
	s_waitcnt lgkmcnt(1)
	v_mfma_f32_16x16x32_f16 v[86:89], v[240:243], v[106:109], v[86:89]
	ds_read_b128 v[240:243], v237 offset:13056
	s_waitcnt lgkmcnt(1)
	v_mfma_f32_16x16x32_f16 v[86:89], v[244:247], v[110:113], v[86:89]
	ds_read_b128 v[244:247], v237 offset:13120
	s_waitcnt lgkmcnt(1)
	v_mfma_f32_16x16x32_f16 v[82:85], v[240:243], v[98:101], v[82:85]
	ds_read_b128 v[240:243], v237 offset:13184
	s_waitcnt lgkmcnt(1)
	v_mfma_f32_16x16x32_f16 v[82:85], v[244:247], v[102:105], v[82:85]
	ds_read_b128 v[244:247], v237 offset:13248
	s_waitcnt lgkmcnt(1)
	v_mfma_f32_16x16x32_f16 v[82:85], v[240:243], v[106:109], v[82:85]
	ds_read_b128 v[240:243], v237 offset:17408
	s_waitcnt lgkmcnt(1)
	v_mfma_f32_16x16x32_f16 v[82:85], v[244:247], v[110:113], v[82:85]
	ds_read_b128 v[244:247], v237 offset:17472
	s_waitcnt lgkmcnt(1)
	v_mfma_f32_16x16x32_f16 v[78:81], v[240:243], v[98:101], v[78:81]
	ds_read_b128 v[240:243], v237 offset:17536
	s_waitcnt lgkmcnt(1)
	v_mfma_f32_16x16x32_f16 v[78:81], v[244:247], v[102:105], v[78:81]
	ds_read_b128 v[244:247], v237 offset:17600
	s_waitcnt lgkmcnt(1)
	v_mfma_f32_16x16x32_f16 v[78:81], v[240:243], v[106:109], v[78:81]
	ds_read_b128 v[240:243], v237 offset:21760
	s_waitcnt lgkmcnt(1)
	v_mfma_f32_16x16x32_f16 v[78:81], v[244:247], v[110:113], v[78:81]
	ds_read_b128 v[244:247], v237 offset:21824
	s_waitcnt lgkmcnt(1)
	v_mfma_f32_16x16x32_f16 v[74:77], v[240:243], v[98:101], v[74:77]
	ds_read_b128 v[240:243], v237 offset:21888
	s_waitcnt lgkmcnt(1)
	v_mfma_f32_16x16x32_f16 v[74:77], v[244:247], v[102:105], v[74:77]
	ds_read_b128 v[244:247], v237 offset:21952
	s_waitcnt lgkmcnt(1)
	v_mfma_f32_16x16x32_f16 v[74:77], v[240:243], v[106:109], v[74:77]
	ds_read_b128 v[240:243], v237 offset:26112
	s_waitcnt lgkmcnt(1)
	v_mfma_f32_16x16x32_f16 v[74:77], v[244:247], v[110:113], v[74:77]
	ds_read_b128 v[244:247], v237 offset:26176
	s_waitcnt lgkmcnt(1)
	v_mfma_f32_16x16x32_f16 v[70:73], v[240:243], v[98:101], v[70:73]
	ds_read_b128 v[240:243], v237 offset:26240
	s_waitcnt lgkmcnt(1)
	v_mfma_f32_16x16x32_f16 v[70:73], v[244:247], v[102:105], v[70:73]
	ds_read_b128 v[244:247], v237 offset:26304
	s_waitcnt lgkmcnt(1)
	v_mfma_f32_16x16x32_f16 v[70:73], v[240:243], v[106:109], v[70:73]
	ds_read_b128 v[240:243], v237 offset:30464
	s_waitcnt lgkmcnt(1)
	v_mfma_f32_16x16x32_f16 v[70:73], v[244:247], v[110:113], v[70:73]
	ds_read_b128 v[244:247], v237 offset:30528
	s_waitcnt lgkmcnt(1)
	v_mfma_f32_16x16x32_f16 v[54:57], v[240:243], v[98:101], v[54:57]
	ds_read_b128 v[240:243], v237 offset:30592
	s_waitcnt lgkmcnt(1)
	v_mfma_f32_16x16x32_f16 v[54:57], v[244:247], v[102:105], v[54:57]
	ds_read_b128 v[244:247], v237 offset:30656
	s_waitcnt lgkmcnt(1)
	v_mfma_f32_16x16x32_f16 v[54:57], v[240:243], v[106:109], v[54:57]
	s_waitcnt vmcnt(0)
	ds_write_b128 v222, v[66:69]
	v_add_u32_e32 v222, v235, v232
	s_waitcnt lgkmcnt(1)
	v_mfma_f32_16x16x32_f16 v[54:57], v[244:247], v[110:113], v[54:57]
	ds_write_b128 v222, v[62:65]
	v_add_u32_e32 v222, v235, v233
	ds_write_b128 v222, v[58:61]
	v_add_u32_e32 v222, v235, v234
	ds_write_b128 v222, v[50:53]
	s_cbranch_scc0 .LBB0_789
	s_ashr_i32 s15, s14, 31
	s_lshl_b64 s[14:15], s[14:15], 16
	v_lshl_add_u64 v[50:51], v[134:135], 0, s[14:15]
	v_lshl_add_u64 v[52:53], v[50:51], 0, v[136:137]
	v_lshl_add_u64 v[58:59], v[50:51], 0, v[138:139]
	global_load_dwordx4 v[66:69], v[52:53], off
	global_load_dwordx4 v[62:65], v[58:59], off
	v_lshl_add_u64 v[52:53], v[50:51], 0, v[140:141]
	v_lshl_add_u64 v[50:51], v[50:51], 0, v[142:143]
	global_load_dwordx4 v[58:61], v[52:53], off
	s_nop 0
	global_load_dwordx4 v[50:53], v[50:51], off
	s_branch .LBB0_789
